# oddprep row pass: remaining lane sums (two 8-lane group sums, the kr block's 64-lane sum) via DPP instead of ds_bpermute steps
# speedup vs baseline: 1.0019x; 1.0019x over previous
; DEVI float bf2f(bf16_t v) { return __uint_as_float(((unsigned)v) << 16); }
; DEVI float wave_sum(float v) { for (int o = 32; o; o >>= 1) v += __shfl_xor(v, o); return v; }
; __device__ __forceinline__ void oddprep_phase(const Params& p) {
;     ...
;       float v = lane < 32 ? bf2f(zr[640 + lane]) : 0.f;
;       const float ss = wave_sum(v * v); const float rs = rsqrtf(ss * (1.0f / 32.0f) + EPS);
;       const float kn = lane < 32 ? v * rs * p.od_g_kr[lane & 31] : 0.f;
.LBB0_1267:
	s_or_b64 exec, exec, s[10:11]
	v_mul_f32_e32 v3, v2, v2
	s_nop 1
	v_add_f32_dpp v3, v3, v3 row_shr:1 row_mask:0xf bank_mask:0xf
	s_nop 1
	v_add_f32_dpp v3, v3, v3 row_shr:2 row_mask:0xf bank_mask:0xf
	s_nop 1
	v_add_f32_dpp v3, v3, v3 row_shr:4 row_mask:0xf bank_mask:0xf
	s_nop 1
	v_add_f32_dpp v3, v3, v3 row_shr:8 row_mask:0xf bank_mask:0xf
	s_nop 1
	v_add_f32_dpp v3, v3, v3 row_bcast:15 row_mask:0xa bank_mask:0xf
	s_nop 1
	v_add_f32_dpp v3, v3, v3 row_bcast:31 row_mask:0xc bank_mask:0xf
	s_nop 0
	v_readlane_b32 s98, v3, 63
	s_nop 1
	v_mov_b32_e32 v3, s98
	v_mov_b32_e32 v5, 0
	s_and_saveexec_b64 s[10:11], s[2:3]
	s_cbranch_execz .LBB0_1269
	s_waitcnt lgkmcnt(0)
	v_add_f32_e32 v1, v3, v5
	v_fmamk_f32 v1, v1, 0x3d000000, v132
	v_cmp_gt_f32_e32 vcc, s81, v1
	v_mul_f32_e32 v3, 0x4b800000, v1
	s_nop 0
	v_cndmask_b32_e32 v1, v1, v3, vcc
	v_rsq_f32_e32 v1, v1
	s_nop 0
	v_mul_f32_e32 v3, 0x45800000, v1
	v_cndmask_b32_e32 v1, v1, v3, vcc
	v_mul_f32_e32 v1, v2, v1
	s_nop 1
	v_mov_b32_e32 v2, v70
	v_mul_f32_e32 v1, v1, v2

; DEVI unsigned pk_bf16(float lo, float hi) { unsigned r; asm("v_cvt_pk_bf16_f32 %0, %1, %2" : "=v"(r) : "v"(lo), "v"(hi)); return r; }
; DEVI float bf_lo(unsigned u) { return __uint_as_float(u << 16); }
; DEVI float bf_hi(unsigned u) { return __uint_as_float(u & 0xffff0000u); }
; __device__ __forceinline__ void oddprep_phase(const Params& p) {
;     ...
; #pragma unroll
;     for (int which = 0; which < 2; ++which) {
;       bf16_t* base = zr + (which ? 1184 : 672) + 8 * lane; const float* gg = (which ? p.od_g_fk : p.od_g_fq) + 8 * (lane & 7);
;       const uint4 u = *(const uint4*)base; const unsigned uu[4] = {u.x, u.y, u.z, u.w};
;       float v[8]; float ss = 0.f;
; #pragma unroll
;       for (int j = 0; j < 4; ++j) { v[2 * j] = bf_lo(uu[j]); v[2 * j + 1] = bf_hi(uu[j]); ss += v[2 * j] * v[2 * j] + v[2 * j + 1] * v[2 * j + 1]; }
;       ss += __shfl_xor(ss, 1); ss += __shfl_xor(ss, 2); ss += __shfl_xor(ss, 4);
;       const float rs = rsqrtf(ss * (1.0f / 64.0f) + EPS);
;       *(uint4*)base = make_uint4(pk_bf16(v[0] * rs * gg[0], v[1] * rs * gg[1]), pk_bf16(v[2] * rs * gg[2], v[3] * rs * gg[3]), pk_bf16(v[4] * rs * gg[4], v[5] * rs * gg[5]), pk_bf16(v[6] * rs * gg[6], v[7] * rs * gg[7]));
;     }
.LBB0_1273:
	s_or_b64 exec, exec, s[10:11]
	v_readlane_b32 s16, v253, 2
	v_readlane_b32 s18, v253, 4
	v_readlane_b32 s19, v253, 5
	s_mov_b32 s10, 0x7896000
	v_readlane_b32 s17, v253, 3
	v_lshl_add_u64 v[0:1], s[18:19], 0, v[30:31]
	v_add_co_u32_e32 v2, vcc, 0x7895000, v0
	s_waitcnt lgkmcnt(0)
	s_nop 0
	v_addc_co_u32_e32 v3, vcc, 0, v1, vcc
	s_waitcnt vmcnt(0)
	v_mov_b64_e32 v[32:33], v[96:97]
	v_mov_b64_e32 v[34:35], v[98:99]
	v_and_b32_e32 v47, 0xffff0000, v33
	v_and_b32_e32 v46, 0xffff0000, v32
	v_lshlrev_b32_e32 v37, 16, v33
	v_lshlrev_b32_e32 v36, 16, v32
	v_pk_mul_f32 v[32:33], v[46:47], v[46:47]
	v_and_b32_e32 v51, 0xffff0000, v35
	v_and_b32_e32 v50, 0xffff0000, v34
	v_pk_fma_f32 v[32:33], v[36:37], v[36:37], v[32:33]
	v_lshlrev_b32_e32 v49, 16, v35
	v_lshlrev_b32_e32 v48, 16, v34
	v_pk_mul_f32 v[34:35], v[50:51], v[50:51]
	v_add_f32_e32 v5, v32, v33
	v_pk_fma_f32 v[34:35], v[48:49], v[48:49], v[34:35]
	s_nop 0
	v_add_f32_e32 v5, v5, v34
	v_add_f32_e32 v5, v5, v35
	s_nop 1
	v_add_f32_dpp v5, v5, v5 quad_perm:[1,0,3,2] row_mask:0xf bank_mask:0xf
	s_nop 1
	v_add_f32_dpp v5, v5, v5 quad_perm:[2,3,0,1] row_mask:0xf bank_mask:0xf
	s_nop 1
	v_add_f32_dpp v5, v5, v5 row_half_mirror row_mask:0xf bank_mask:0xf
	v_fmamk_f32 v5, v5, 0x3c800000, v132
	v_cmp_gt_f32_e32 vcc, s81, v5
	v_mul_f32_e32 v32, 0x4b800000, v5
	s_nop 0
	v_cndmask_b32_e32 v5, v5, v32, vcc
	v_rsq_f32_e32 v5, v5
	s_nop 0
	v_mul_f32_e32 v32, 0x45800000, v5
	v_cndmask_b32_e32 v5, v5, v32, vcc
	v_mul_f32_e32 v36, v5, v36
	v_mul_f32_e32 v45, v5, v48
	s_nop 1
	v_mov_b64_e32 v[32:33], v[76:77]
	v_mov_b64_e32 v[34:35], v[78:79]
	v_mul_f32_e32 v32, v32, v36
	v_mul_f32_e32 v36, v5, v46
	v_mul_f32_e32 v33, v33, v36
	v_cvt_pk_bf16_f32 v32, v32, v33
	v_mul_f32_e32 v33, v5, v37
	v_mul_f32_e32 v33, v34, v33
	v_mul_f32_e32 v34, v5, v47
	v_mul_f32_e32 v34, v35, v34
	v_cvt_pk_bf16_f32 v33, v33, v34
	s_nop 1
	v_mov_b64_e32 v[34:35], v[80:81]
	v_mov_b64_e32 v[36:37], v[82:83]
	v_mul_f32_e32 v34, v34, v45
	v_mul_f32_e32 v45, v5, v50
	v_mul_f32_e32 v35, v35, v45
	v_cvt_pk_bf16_f32 v34, v34, v35
	v_mul_f32_e32 v35, v5, v49
	v_mul_f32_e32 v35, v36, v35
	v_mul_f32_e32 v5, v5, v51
	v_mul_f32_e32 v5, v37, v5
	v_cvt_pk_bf16_f32 v35, v35, v5
	global_store_dwordx4 v[2:3], v[32:35], off offset:3648
	s_nop 1
	v_add_co_u32_e32 v32, vcc, s10, v0
	s_nop 1
	v_addc_co_u32_e32 v33, vcc, 0, v1, vcc
	s_waitcnt vmcnt(0)
	v_mov_b64_e32 v[0:1], v[100:101]
	v_mov_b64_e32 v[2:3], v[102:103]
	v_lshlrev_b32_e32 v37, 16, v1
	v_lshlrev_b32_e32 v36, 16, v0
	v_and_b32_e32 v1, 0xffff0000, v1
	v_and_b32_e32 v0, 0xffff0000, v0
	v_pk_mul_f32 v[34:35], v[0:1], v[0:1]
	s_nop 0
	v_pk_fma_f32 v[46:47], v[36:37], v[36:37], v[34:35]
	v_lshlrev_b32_e32 v35, 16, v3
	v_lshlrev_b32_e32 v34, 16, v2
	v_and_b32_e32 v3, 0xffff0000, v3
	v_and_b32_e32 v2, 0xffff0000, v2
	v_pk_mul_f32 v[48:49], v[2:3], v[2:3]
	v_add_f32_e32 v5, v46, v47
	v_pk_fma_f32 v[48:49], v[34:35], v[34:35], v[48:49]
	s_nop 0
	v_add_f32_e32 v5, v5, v48
	v_add_f32_e32 v5, v5, v49
	s_nop 1
	v_add_f32_dpp v5, v5, v5 quad_perm:[1,0,3,2] row_mask:0xf bank_mask:0xf
	s_nop 1
	v_add_f32_dpp v5, v5, v5 quad_perm:[2,3,0,1] row_mask:0xf bank_mask:0xf
	s_nop 1
	v_add_f32_dpp v5, v5, v5 row_half_mirror row_mask:0xf bank_mask:0xf
	v_fmamk_f32 v5, v5, 0x3c800000, v132
	v_cmp_gt_f32_e32 vcc, s81, v5
	v_mul_f32_e32 v45, 0x4b800000, v5
	s_nop 0
	v_cndmask_b32_e32 v5, v5, v45, vcc
	v_rsq_f32_e32 v5, v5
	s_nop 0
	v_mul_f32_e32 v45, 0x45800000, v5
	v_cndmask_b32_e32 v5, v5, v45, vcc
	v_mul_f32_e32 v36, v5, v36
	v_mul_f32_e32 v0, v5, v0
	v_mul_f32_e32 v1, v5, v1
	v_mul_f32_e32 v34, v5, v34
	v_mul_f32_e32 v2, v5, v2
	v_mul_f32_e32 v3, v5, v3
	s_nop 1
	v_mov_b64_e32 v[46:47], v[84:85]
	v_mov_b64_e32 v[48:49], v[86:87]
	v_mul_f32_e32 v36, v46, v36
	v_mul_f32_e32 v0, v47, v0
	v_cvt_pk_bf16_f32 v0, v36, v0
	v_mul_f32_e32 v36, v5, v37
	v_mul_f32_e32 v36, v48, v36
	v_mul_f32_e32 v1, v49, v1
	v_cvt_pk_bf16_f32 v1, v36, v1
	s_nop 1
	v_mov_b64_e32 v[46:47], v[88:89]
	v_mov_b64_e32 v[48:49], v[90:91]
	v_mul_f32_e32 v34, v46, v34
	v_mul_f32_e32 v2, v47, v2
	v_cvt_pk_bf16_f32 v2, v34, v2
	v_mul_f32_e32 v34, v5, v35
	v_mul_f32_e32 v3, v49, v3
	v_mul_f32_e32 v34, v48, v34
	v_cvt_pk_bf16_f32 v3, v34, v3
	global_store_dwordx4 v[32:33], v[0:3], off offset:576
	s_and_saveexec_b64 s[10:11], s[6:7]
	s_cbranch_execz .LBB0_1262
	v_readlane_b32 s16, v253, 2
	v_readlane_b32 s18, v253, 4
	v_readlane_b32 s19, v253, 5
	s_mov_b32 s16, 0xbfb8aa3b
	v_readlane_b32 s17, v253, 3
	v_lshl_add_u64 v[0:1], s[18:19], 0, v[22:23]
	s_waitcnt vmcnt(0)
	v_mov_b32_e32 v2, v109
	v_mov_b32_e32 v3, v110
	v_add_f32_e32 v2, v2, v3
	v_mul_f32_e64 v3, |v2|, s16
	v_exp_f32_e32 v3, v3
	v_min_f32_e32 v2, 0, v2
	v_add_f32_e32 v3, 1.0, v3
	v_log_f32_e32 v3, v3
	s_nop 0
	v_fmac_f32_e32 v2, 0xbf317218, v3
	global_store_dword v[0:1], v2, off
	s_branch .LBB0_1262
